# attention phase: static s_setprio 1 for waves 4-7 (on top of scan rewrite)
# baseline (speedup 1.0000x reference)
.LBB0_135:
	v_readlane_b32 s0, v249, 27
	s_nop 3
	s_cmpk_lt_u32 s0, 0x100
	s_cbranch_scc1 .Lattn_prio_done
	s_setprio 1

.LBB0_233:
	s_setprio 0
	v_readlane_b32 s0, v250, 5
	v_readlane_b32 s1, v250, 6
	s_ashr_i32 s1, s0, 31
	v_writelane_b32 v250, s0, 5
	v_readlane_b32 s2, v251, 38
	v_mov_b32_e32 v66, 0
	v_writelane_b32 v250, s1, 6
	s_lshl_b64 s[0:1], s[0:1], 2
	s_add_u32 s16, s2, s0
	v_readlane_b32 s0, v251, 39
	s_addc_u32 s17, s0, s1
	s_barrier
	s_and_saveexec_b64 s[0:1], s[40:41]
	s_cbranch_execz .LBB0_237
	s_mov_b64 s[28:29], exec
	v_mbcnt_lo_u32_b32 v0, s28, 0
	v_mbcnt_hi_u32_b32 v0, s29, v0
	v_cmp_eq_u32_e32 vcc, 0, v0
	s_and_saveexec_b64 s[22:23], vcc
	s_cbranch_execz .LBB0_236
	s_bcnt1_i32_b64 s4, s[28:29]
	v_mov_b32_e32 v1, s4
	global_atomic_add v1, v65, v1, s[16:17] sc0
